# hierarchical barriers S1-S3: first arriver of an XCD also starts an L2 write-back (pre-flush)
# baseline (speedup 1.0000x reference)
; __device__ __forceinline__ unsigned xb_ld(unsigned* p)              { return __hip_atomic_load(p, __ATOMIC_RELAXED, __HIP_MEMORY_SCOPE_AGENT); }
; __device__ __forceinline__ unsigned xb_add(unsigned* p, unsigned v) { return __hip_atomic_fetch_add(p, v, __ATOMIC_RELAXED, __HIP_MEMORY_SCOPE_AGENT); }
; #define XB_SPIN(cond, bar) do { unsigned _sp = 0; while (cond) { __builtin_amdgcn_s_sleep(1); \
;     if ((++_sp & 255u) == 0u) { if (xb_ld(&(bar)[XB_TMO])) break; if (_sp > XB_SPIN_CAP) { atomicAdd(&(bar)[XB_TMO], 1u); break; } } } } while (0)
; __device__ __forceinline__ void xcd_barrier(const XcdBarrier& b) {
;     ...
;         const unsigned old = xb_add(&bar[XB_XSUB(b.x)], 1u);
;         const unsigned gen = old / nloc;
;         if (old + 1u == (gen + 1u) * nloc) {
;             __builtin_amdgcn_fence(__ATOMIC_RELEASE, "agent");
;             asm volatile("s_waitcnt vmcnt(0)" ::: "memory");
;             const unsigned og = xb_add(&bar[XB_TOP], 1u);
;             const unsigned tg = og / nx;
;             if (og + 1u == (tg + 1u) * nx) xb_add(&bar[XB_TOPGEN], 1u);
;             else XB_SPIN(xb_ld(&bar[XB_TOPGEN]) == tg, bar);
;             __builtin_amdgcn_fence(__ATOMIC_ACQUIRE, "agent");
;             xb_add(&bar[XB_XGEN(b.x)], 1u);
;             asm volatile("s_waitcnt vmcnt(0)" ::: "memory");
;         } else {
;             XB_SPIN(xb_ld(&bar[XB_XGEN(b.x)]) == gen, bar);
;             __builtin_amdgcn_fence(__ATOMIC_ACQUIRE, "agent");
;             asm volatile("s_waitcnt vmcnt(0)" ::: "memory");
.LBB0_119:
	s_or_b64 exec, exec, s[8:9]
	v_cvt_f32_u32_e32 v5, v3
	s_waitcnt vmcnt(0)
	v_readfirstlane_b32 s3, v4
	v_sub_u32_e32 v4, 0, v3
	v_rcp_iflag_f32_e32 v5, v5
	v_add_u32_e32 v6, s3, v2
	v_mul_f32_e32 v5, 0x4f7ffffe, v5
	v_cvt_u32_f32_e32 v5, v5
	v_mul_lo_u32 v2, v4, v5
	v_mul_hi_u32 v2, v5, v2
	v_add_u32_e32 v2, v5, v2
	v_mul_hi_u32 v2, v6, v2
	v_mul_lo_u32 v4, v2, v3
	v_sub_u32_e32 v4, v6, v4
	v_add_u32_e32 v5, 1, v2
	v_cmp_ge_u32_e32 vcc, v4, v3
	s_nop 1
	v_cndmask_b32_e32 v2, v2, v5, vcc
	v_sub_u32_e32 v5, v4, v3
	v_cndmask_b32_e32 v4, v4, v5, vcc
	v_add_u32_e32 v5, 1, v2
	v_cmp_ge_u32_e32 vcc, v4, v3
	v_add_u32_e32 v4, 1, v6
	s_nop 0
	v_cndmask_b32_e32 v2, v2, v5, vcc
	v_mul_lo_u32 v5, v3, v2
	v_add_u32_e32 v3, v5, v3
	v_cmp_ne_u32_e32 vcc, v4, v3
	s_and_saveexec_b64 s[6:7], vcc
	s_xor_b64 s[6:7], exec, s[6:7]
	s_cbranch_execz .LBB0_133
	s_waitcnt lgkmcnt(0)
	buffer_inv sc1
	v_cmp_eq_u32_e32 vcc, v6, v5
	s_cbranch_vccz .Lpfw1
	buffer_wbl2 sc1
.Lpfw1:
	s_add_u32 s12, s60, 0x7400
	s_addc_u32 s13, s61, 0
	v_add_u32_e32 v2, 1, v2
	v_mul_lo_u32 v2, v2, v1
	v_mov_b32_e32 v1, 0
	global_load_dword v1, v1, s[12:13] sc1
	s_waitcnt vmcnt(0)
	v_cmp_lt_u32_e32 vcc, v1, v2
	s_and_saveexec_b64 s[8:9], vcc
	s_cbranch_execz .LBB0_132
	s_add_u32 s10, s60, 0x4200
	s_addc_u32 s11, s61, 0
	s_mov_b32 s3, 1
	s_mov_b64 s[16:17], 0
	v_mov_b32_e32 v1, 0
	s_branch .LBB0_123

; __device__ __forceinline__ unsigned xb_ld(unsigned* p)              { return __hip_atomic_load(p, __ATOMIC_RELAXED, __HIP_MEMORY_SCOPE_AGENT); }
; __device__ __forceinline__ unsigned xb_add(unsigned* p, unsigned v) { return __hip_atomic_fetch_add(p, v, __ATOMIC_RELAXED, __HIP_MEMORY_SCOPE_AGENT); }
; #define XB_SPIN(cond, bar) do { unsigned _sp = 0; while (cond) { __builtin_amdgcn_s_sleep(1); \
;     if ((++_sp & 255u) == 0u) { if (xb_ld(&(bar)[XB_TMO])) break; if (_sp > XB_SPIN_CAP) { atomicAdd(&(bar)[XB_TMO], 1u); break; } } } } while (0)
; __device__ __forceinline__ void xcd_barrier(const XcdBarrier& b) {
;     ...
;         const unsigned old = xb_add(&bar[XB_XSUB(b.x)], 1u);
;         const unsigned gen = old / nloc;
;         if (old + 1u == (gen + 1u) * nloc) {
;             __builtin_amdgcn_fence(__ATOMIC_RELEASE, "agent");
;             asm volatile("s_waitcnt vmcnt(0)" ::: "memory");
;             const unsigned og = xb_add(&bar[XB_TOP], 1u);
;             const unsigned tg = og / nx;
;             if (og + 1u == (tg + 1u) * nx) xb_add(&bar[XB_TOPGEN], 1u);
;             else XB_SPIN(xb_ld(&bar[XB_TOPGEN]) == tg, bar);
;             __builtin_amdgcn_fence(__ATOMIC_ACQUIRE, "agent");
;             xb_add(&bar[XB_XGEN(b.x)], 1u);
;             asm volatile("s_waitcnt vmcnt(0)" ::: "memory");
;         } else {
;             XB_SPIN(xb_ld(&bar[XB_XGEN(b.x)]) == gen, bar);
;             __builtin_amdgcn_fence(__ATOMIC_ACQUIRE, "agent");
;             asm volatile("s_waitcnt vmcnt(0)" ::: "memory");
.LBB0_191:
	s_or_b64 exec, exec, s[6:7]
	v_cvt_f32_u32_e32 v5, v3
	s_waitcnt vmcnt(0)
	v_readfirstlane_b32 s4, v4
	v_sub_u32_e32 v4, 0, v3
	v_rcp_iflag_f32_e32 v5, v5
	v_add_u32_e32 v6, s4, v2
	v_mul_f32_e32 v5, 0x4f7ffffe, v5
	v_cvt_u32_f32_e32 v5, v5
	v_mul_lo_u32 v2, v4, v5
	v_mul_hi_u32 v2, v5, v2
	v_add_u32_e32 v2, v5, v2
	v_mul_hi_u32 v2, v6, v2
	v_mul_lo_u32 v4, v2, v3
	v_sub_u32_e32 v4, v6, v4
	v_add_u32_e32 v5, 1, v2
	v_cmp_ge_u32_e32 vcc, v4, v3
	s_nop 1
	v_cndmask_b32_e32 v2, v2, v5, vcc
	v_sub_u32_e32 v5, v4, v3
	v_cndmask_b32_e32 v4, v4, v5, vcc
	v_add_u32_e32 v5, 1, v2
	v_cmp_ge_u32_e32 vcc, v4, v3
	v_add_u32_e32 v4, 1, v6
	s_nop 0
	v_cndmask_b32_e32 v2, v2, v5, vcc
	v_mul_lo_u32 v5, v3, v2
	v_add_u32_e32 v3, v5, v3
	v_cmp_ne_u32_e32 vcc, v4, v3
	s_and_saveexec_b64 s[4:5], vcc
	s_xor_b64 s[4:5], exec, s[4:5]
	s_cbranch_execz .LBB0_205
	s_waitcnt lgkmcnt(0)
	buffer_inv sc1
	v_cmp_eq_u32_e32 vcc, v6, v5
	s_cbranch_vccz .Lpfw2
	buffer_wbl2 sc1
.Lpfw2:
	s_add_u32 s8, s34, 0x3400
	s_addc_u32 s9, s35, 0
	v_add_u32_e32 v2, 1, v2
	v_mul_lo_u32 v2, v2, v1
	v_mov_b32_e32 v1, 0
	global_load_dword v1, v1, s[8:9] sc1
	s_waitcnt vmcnt(0)
	v_cmp_lt_u32_e32 vcc, v1, v2
	s_and_saveexec_b64 s[6:7], vcc
	s_cbranch_execz .LBB0_204
	s_mov_b32 s14, 1
	s_mov_b64 s[10:11], 0
	v_mov_b32_e32 v1, 0
	s_branch .LBB0_195

; __device__ __forceinline__ unsigned xb_ld(unsigned* p)              { return __hip_atomic_load(p, __ATOMIC_RELAXED, __HIP_MEMORY_SCOPE_AGENT); }
; __device__ __forceinline__ unsigned xb_add(unsigned* p, unsigned v) { return __hip_atomic_fetch_add(p, v, __ATOMIC_RELAXED, __HIP_MEMORY_SCOPE_AGENT); }
; #define XB_SPIN(cond, bar) do { unsigned _sp = 0; while (cond) { __builtin_amdgcn_s_sleep(1); \
;     if ((++_sp & 255u) == 0u) { if (xb_ld(&(bar)[XB_TMO])) break; if (_sp > XB_SPIN_CAP) { atomicAdd(&(bar)[XB_TMO], 1u); break; } } } } while (0)
; __device__ __forceinline__ void xcd_barrier(const XcdBarrier& b) {
;     ...
;         const unsigned old = xb_add(&bar[XB_XSUB(b.x)], 1u);
;         const unsigned gen = old / nloc;
;         if (old + 1u == (gen + 1u) * nloc) {
;             __builtin_amdgcn_fence(__ATOMIC_RELEASE, "agent");
;             asm volatile("s_waitcnt vmcnt(0)" ::: "memory");
;             const unsigned og = xb_add(&bar[XB_TOP], 1u);
;             const unsigned tg = og / nx;
;             if (og + 1u == (tg + 1u) * nx) xb_add(&bar[XB_TOPGEN], 1u);
;             else XB_SPIN(xb_ld(&bar[XB_TOPGEN]) == tg, bar);
;             __builtin_amdgcn_fence(__ATOMIC_ACQUIRE, "agent");
;             xb_add(&bar[XB_XGEN(b.x)], 1u);
;             asm volatile("s_waitcnt vmcnt(0)" ::: "memory");
;         } else {
;             XB_SPIN(xb_ld(&bar[XB_XGEN(b.x)]) == gen, bar);
;             __builtin_amdgcn_fence(__ATOMIC_ACQUIRE, "agent");
;             asm volatile("s_waitcnt vmcnt(0)" ::: "memory");
.LBB0_401:
	s_or_b64 exec, exec, s[8:9]
	v_cvt_f32_u32_e32 v5, v3
	s_waitcnt vmcnt(0)
	v_readfirstlane_b32 s6, v4
	v_sub_u32_e32 v4, 0, v3
	v_rcp_iflag_f32_e32 v5, v5
	v_add_u32_e32 v6, s6, v2
	v_mul_f32_e32 v5, 0x4f7ffffe, v5
	v_cvt_u32_f32_e32 v5, v5
	v_mul_lo_u32 v2, v4, v5
	v_mul_hi_u32 v2, v5, v2
	v_add_u32_e32 v2, v5, v2
	v_mul_hi_u32 v2, v6, v2
	v_mul_lo_u32 v4, v2, v3
	v_sub_u32_e32 v4, v6, v4
	v_add_u32_e32 v5, 1, v2
	v_cmp_ge_u32_e32 vcc, v4, v3
	s_nop 1
	v_cndmask_b32_e32 v2, v2, v5, vcc
	v_sub_u32_e32 v5, v4, v3
	v_cndmask_b32_e32 v4, v4, v5, vcc
	v_add_u32_e32 v5, 1, v2
	v_cmp_ge_u32_e32 vcc, v4, v3
	v_add_u32_e32 v4, 1, v6
	s_nop 0
	v_cndmask_b32_e32 v2, v2, v5, vcc
	v_mul_lo_u32 v5, v3, v2
	v_add_u32_e32 v3, v5, v3
	v_cmp_ne_u32_e32 vcc, v4, v3
	s_and_saveexec_b64 s[6:7], vcc
	s_xor_b64 s[6:7], exec, s[6:7]
	s_cbranch_execz .LBB0_415
	s_waitcnt lgkmcnt(0)
	buffer_inv sc1
	v_cmp_eq_u32_e32 vcc, v6, v5
	s_cbranch_vccz .Lpfw3
	buffer_wbl2 sc1
.Lpfw3:
	s_add_u32 s10, s34, 0x3400
	s_addc_u32 s11, s35, 0
	v_add_u32_e32 v2, 1, v2
	v_mul_lo_u32 v2, v2, v1
	v_mov_b32_e32 v1, 0
	global_load_dword v1, v1, s[10:11] sc1
	s_waitcnt vmcnt(0)
	v_cmp_lt_u32_e32 vcc, v1, v2
	s_and_saveexec_b64 s[8:9], vcc
	s_cbranch_execz .LBB0_414
	s_mov_b32 s14, 1
	s_mov_b64 s[12:13], 0
	v_mov_b32_e32 v1, 0
	s_branch .LBB0_405
